# phase_in tail p->bf16 copy moved to the 128 workgroups that have only 5 tile rounds, loads batched 8 items deep
# speedup vs baseline: 1.0055x; 1.0010x over previous
; DI int vbid() { return (int)blockIdx.x * 2 + half_(); }
; DI int vgrid() { return (int)gridDim.x * 2; }
; DI u32x4 pack8(const float* f) { u32x4 o; o.x = pack2(f[0], f[1]); o.y = pack2(f[2], f[3]); o.z = pack2(f[4], f[5]); o.w = pack2(f[6], f[7]); return o; }
; DI void phase_in(PREF p, int l, unsigned char* lds_all) {
;     ...
;   }
;   __syncthreads();
;   const int gtid = vbid() * 256 + tid, gsz = vgrid() * 256;
;   const float* ps = p.p + (size_t)l * T_ * 256;
;   for (int idx = gtid; idx < T_ * 256 / 8; idx += gsz) {
;     const float4* s = (const float4*)(ps + (size_t)idx * 8);
;     float4 a = s[0], b = s[1];
;     float v[8] = {a.x, a.y, a.z, a.w, b.x, b.y, b.z, b.w};
;     *(u32x4*)(p.pb + (size_t)idx * 8) = pack8(v);
;   }
; }
.LBB0_483:
	v_readlane_b32 s0, v254, 32
	s_cmpk_lg_u32 s0, 0x100
	s_cbranch_scc1 .Lmy_pb_orig
	s_waitcnt vmcnt(0) lgkmcnt(0)
	s_barrier
	v_readlane_b32 s0, v254, 0
	s_cmpk_lt_u32 s0, 0x80
	s_cbranch_scc1 .Lmy_pb_done
; DI int vbid() { return (int)blockIdx.x * 2 + half_(); }
; DI int vgrid() { return (int)gridDim.x * 2; }
; DI u32x4 pack8(const float* f) { u32x4 o; o.x = pack2(f[0], f[1]); o.y = pack2(f[2], f[3]); o.z = pack2(f[4], f[5]); o.w = pack2(f[6], f[7]); return o; }
; DI void phase_in(PREF p, int l, unsigned char* lds_all) {
;     ...
;   const int gtid = vbid() * 256 + tid, gsz = vgrid() * 256;
;   const float* ps = p.p + (size_t)l * T_ * 256;
;   for (int idx = gtid; idx < T_ * 256 / 8; idx += gsz) {
;     const float4* s = (const float4*)(ps + (size_t)idx * 8);
;     float4 a = s[0], b = s[1];
;     float v[8] = {a.x, a.y, a.z, a.w, b.x, b.y, b.z, b.w};
;     *(u32x4*)(p.pb + (size_t)idx * 8) = pack8(v);
;   }
	s_sub_i32 s0, s0, 0x80
	s_lshl_b32 s0, s0, 9
	v_add_u32_e32 v2, s0, v168
	v_mov_b32_e32 v3, 0
	v_readlane_b32 s14, v254, 26
	v_readlane_b32 s16, v254, 28
	v_readlane_b32 s15, v254, 27
	v_readlane_b32 s17, v254, 29
	v_readlane_b32 s12, v254, 46
	v_readlane_b32 s13, v254, 47
	s_load_dwordx2 s[0:1], s[12:13], 0x8
	s_lshl_b64 s[10:11], s[56:57], 25
	s_load_dwordx2 s[12:13], s[12:13], 0x138
	v_lshlrev_b64 v[6:7], 5, v[2:3]
	s_waitcnt lgkmcnt(0)
	s_add_u32 s0, s0, s10
	s_addc_u32 s1, s1, s11
	v_lshl_add_u64 v[6:7], s[0:1], 0, v[6:7]
	v_lshl_add_u64 v[4:5], v[2:3], 4, s[12:13]
	s_mov_b64 s[10:11], 0x100000
	global_load_dwordx4 v[80:83], v[6:7], off
	global_load_dwordx4 v[84:87], v[6:7], off offset:16
	v_lshl_add_u64 v[6:7], v[6:7], 0, s[14:15]
	global_load_dwordx4 v[88:91], v[6:7], off
	global_load_dwordx4 v[92:95], v[6:7], off offset:16
	v_lshl_add_u64 v[6:7], v[6:7], 0, s[14:15]
	global_load_dwordx4 v[96:99], v[6:7], off
	global_load_dwordx4 v[100:103], v[6:7], off offset:16
	v_lshl_add_u64 v[6:7], v[6:7], 0, s[14:15]
	global_load_dwordx4 v[104:107], v[6:7], off
	global_load_dwordx4 v[108:111], v[6:7], off offset:16
	v_lshl_add_u64 v[6:7], v[6:7], 0, s[14:15]
	global_load_dwordx4 v[112:115], v[6:7], off
	global_load_dwordx4 v[120:123], v[6:7], off offset:16
	v_lshl_add_u64 v[6:7], v[6:7], 0, s[14:15]
	global_load_dwordx4 v[124:127], v[6:7], off
	global_load_dwordx4 v[128:131], v[6:7], off offset:16
	v_lshl_add_u64 v[6:7], v[6:7], 0, s[14:15]
	global_load_dwordx4 v[132:135], v[6:7], off
	global_load_dwordx4 v[136:139], v[6:7], off offset:16
	v_lshl_add_u64 v[6:7], v[6:7], 0, s[14:15]
	global_load_dwordx4 v[144:147], v[6:7], off
	global_load_dwordx4 v[148:151], v[6:7], off offset:16
	v_lshl_add_u64 v[6:7], v[6:7], 0, s[14:15]
	s_waitcnt vmcnt(14)
	v_cvt_pk_bf16_f32 v80, v80, v81
	v_cvt_pk_bf16_f32 v81, v82, v83
	v_cvt_pk_bf16_f32 v82, v84, v85
	v_cvt_pk_bf16_f32 v83, v86, v87
	global_store_dwordx4 v[4:5], v[80:83], off
	v_lshl_add_u64 v[4:5], v[4:5], 0, s[10:11]
	s_waitcnt vmcnt(13)
	v_cvt_pk_bf16_f32 v88, v88, v89
	v_cvt_pk_bf16_f32 v89, v90, v91
	v_cvt_pk_bf16_f32 v90, v92, v93
	v_cvt_pk_bf16_f32 v91, v94, v95
	global_store_dwordx4 v[4:5], v[88:91], off
	v_lshl_add_u64 v[4:5], v[4:5], 0, s[10:11]
	s_waitcnt vmcnt(12)
	v_cvt_pk_bf16_f32 v96, v96, v97
	v_cvt_pk_bf16_f32 v97, v98, v99
	v_cvt_pk_bf16_f32 v98, v100, v101
	v_cvt_pk_bf16_f32 v99, v102, v103
	global_store_dwordx4 v[4:5], v[96:99], off
	v_lshl_add_u64 v[4:5], v[4:5], 0, s[10:11]
	s_waitcnt vmcnt(11)
	v_cvt_pk_bf16_f32 v104, v104, v105
	v_cvt_pk_bf16_f32 v105, v106, v107
	v_cvt_pk_bf16_f32 v106, v108, v109
	v_cvt_pk_bf16_f32 v107, v110, v111
	global_store_dwordx4 v[4:5], v[104:107], off
	v_lshl_add_u64 v[4:5], v[4:5], 0, s[10:11]
	s_waitcnt vmcnt(10)
	v_cvt_pk_bf16_f32 v112, v112, v113
	v_cvt_pk_bf16_f32 v113, v114, v115
	v_cvt_pk_bf16_f32 v114, v120, v121
	v_cvt_pk_bf16_f32 v115, v122, v123
	global_store_dwordx4 v[4:5], v[112:115], off
	v_lshl_add_u64 v[4:5], v[4:5], 0, s[10:11]
	s_waitcnt vmcnt(9)
	v_cvt_pk_bf16_f32 v124, v124, v125
	v_cvt_pk_bf16_f32 v125, v126, v127
	v_cvt_pk_bf16_f32 v126, v128, v129
	v_cvt_pk_bf16_f32 v127, v130, v131
	global_store_dwordx4 v[4:5], v[124:127], off
	v_lshl_add_u64 v[4:5], v[4:5], 0, s[10:11]
	s_waitcnt vmcnt(8)
	v_cvt_pk_bf16_f32 v132, v132, v133
	v_cvt_pk_bf16_f32 v133, v134, v135
	v_cvt_pk_bf16_f32 v134, v136, v137
	v_cvt_pk_bf16_f32 v135, v138, v139
	global_store_dwordx4 v[4:5], v[132:135], off
	v_lshl_add_u64 v[4:5], v[4:5], 0, s[10:11]
	s_waitcnt vmcnt(7)
	v_cvt_pk_bf16_f32 v144, v144, v145
	v_cvt_pk_bf16_f32 v145, v146, v147
	v_cvt_pk_bf16_f32 v146, v148, v149
	v_cvt_pk_bf16_f32 v147, v150, v151
	global_store_dwordx4 v[4:5], v[144:147], off
	v_lshl_add_u64 v[4:5], v[4:5], 0, s[10:11]
	global_load_dwordx4 v[80:83], v[6:7], off
	global_load_dwordx4 v[84:87], v[6:7], off offset:16
	v_lshl_add_u64 v[6:7], v[6:7], 0, s[14:15]
	global_load_dwordx4 v[88:91], v[6:7], off
	global_load_dwordx4 v[92:95], v[6:7], off offset:16
	v_lshl_add_u64 v[6:7], v[6:7], 0, s[14:15]
	global_load_dwordx4 v[96:99], v[6:7], off
	global_load_dwordx4 v[100:103], v[6:7], off offset:16
	v_lshl_add_u64 v[6:7], v[6:7], 0, s[14:15]
	global_load_dwordx4 v[104:107], v[6:7], off
	global_load_dwordx4 v[108:111], v[6:7], off offset:16
	v_lshl_add_u64 v[6:7], v[6:7], 0, s[14:15]
	global_load_dwordx4 v[112:115], v[6:7], off
	global_load_dwordx4 v[120:123], v[6:7], off offset:16
	v_lshl_add_u64 v[6:7], v[6:7], 0, s[14:15]
	global_load_dwordx4 v[124:127], v[6:7], off
	global_load_dwordx4 v[128:131], v[6:7], off offset:16
	v_lshl_add_u64 v[6:7], v[6:7], 0, s[14:15]
	global_load_dwordx4 v[132:135], v[6:7], off
	global_load_dwordx4 v[136:139], v[6:7], off offset:16
	v_lshl_add_u64 v[6:7], v[6:7], 0, s[14:15]
	global_load_dwordx4 v[144:147], v[6:7], off
	global_load_dwordx4 v[148:151], v[6:7], off offset:16
	v_lshl_add_u64 v[6:7], v[6:7], 0, s[14:15]
	s_waitcnt vmcnt(14)
	v_cvt_pk_bf16_f32 v80, v80, v81
	v_cvt_pk_bf16_f32 v81, v82, v83
	v_cvt_pk_bf16_f32 v82, v84, v85
	v_cvt_pk_bf16_f32 v83, v86, v87
	global_store_dwordx4 v[4:5], v[80:83], off
	v_lshl_add_u64 v[4:5], v[4:5], 0, s[10:11]
	s_waitcnt vmcnt(13)
	v_cvt_pk_bf16_f32 v88, v88, v89
	v_cvt_pk_bf16_f32 v89, v90, v91
	v_cvt_pk_bf16_f32 v90, v92, v93
	v_cvt_pk_bf16_f32 v91, v94, v95
	global_store_dwordx4 v[4:5], v[88:91], off
	v_lshl_add_u64 v[4:5], v[4:5], 0, s[10:11]
	s_waitcnt vmcnt(12)
	v_cvt_pk_bf16_f32 v96, v96, v97
	v_cvt_pk_bf16_f32 v97, v98, v99
	v_cvt_pk_bf16_f32 v98, v100, v101
	v_cvt_pk_bf16_f32 v99, v102, v103
	global_store_dwordx4 v[4:5], v[96:99], off
	v_lshl_add_u64 v[4:5], v[4:5], 0, s[10:11]
	s_waitcnt vmcnt(11)
	v_cvt_pk_bf16_f32 v104, v104, v105
	v_cvt_pk_bf16_f32 v105, v106, v107
	v_cvt_pk_bf16_f32 v106, v108, v109
	v_cvt_pk_bf16_f32 v107, v110, v111
	global_store_dwordx4 v[4:5], v[104:107], off
	v_lshl_add_u64 v[4:5], v[4:5], 0, s[10:11]
	s_waitcnt vmcnt(10)
	v_cvt_pk_bf16_f32 v112, v112, v113
	v_cvt_pk_bf16_f32 v113, v114, v115
	v_cvt_pk_bf16_f32 v114, v120, v121
	v_cvt_pk_bf16_f32 v115, v122, v123
	global_store_dwordx4 v[4:5], v[112:115], off
	v_lshl_add_u64 v[4:5], v[4:5], 0, s[10:11]
	s_waitcnt vmcnt(9)
	v_cvt_pk_bf16_f32 v124, v124, v125
	v_cvt_pk_bf16_f32 v125, v126, v127
	v_cvt_pk_bf16_f32 v126, v128, v129
	v_cvt_pk_bf16_f32 v127, v130, v131
	global_store_dwordx4 v[4:5], v[124:127], off
	v_lshl_add_u64 v[4:5], v[4:5], 0, s[10:11]
	s_waitcnt vmcnt(8)
	v_cvt_pk_bf16_f32 v132, v132, v133
	v_cvt_pk_bf16_f32 v133, v134, v135
	v_cvt_pk_bf16_f32 v134, v136, v137
	v_cvt_pk_bf16_f32 v135, v138, v139
	global_store_dwordx4 v[4:5], v[132:135], off
	v_lshl_add_u64 v[4:5], v[4:5], 0, s[10:11]
	s_waitcnt vmcnt(7)
	v_cvt_pk_bf16_f32 v144, v144, v145
	v_cvt_pk_bf16_f32 v145, v146, v147
	v_cvt_pk_bf16_f32 v146, v148, v149
	v_cvt_pk_bf16_f32 v147, v150, v151
	global_store_dwordx4 v[4:5], v[144:147], off
	v_lshl_add_u64 v[4:5], v[4:5], 0, s[10:11]
	s_branch .Lmy_pb_done

; DI u32x4 pack8(const float* f) { u32x4 o; o.x = pack2(f[0], f[1]); o.y = pack2(f[2], f[3]); o.z = pack2(f[4], f[5]); o.w = pack2(f[6], f[7]); return o; }
; DI void phase_in(PREF p, int l, unsigned char* lds_all) {
;     ...
;   for (int idx = gtid; idx < T_ * 256 / 8; idx += gsz) {
;     const float4* s = (const float4*)(ps + (size_t)idx * 8);
;     float4 a = s[0], b = s[1];
;     float v[8] = {a.x, a.y, a.z, a.w, b.x, b.y, b.z, b.w};
;     *(u32x4*)(p.pb + (size_t)idx * 8) = pack8(v);
;   }
; }
.LBB0_486:
	s_or_b64 exec, exec, s[8:9]
.Lmy_pb_done:
	v_readlane_b32 s10, v254, 46
	v_readlane_b32 s11, v254, 47
.LBB0_487:
	s_getpc_b64 s[98:99]
